# 64x64 GEMM units: next K-chunk global loads issued behind the LDS writes, in front of the lgkmcnt drain and the workgroup barrier
# baseline (speedup 1.0000x reference)
.LBB0_544:
	s_or_b64 exec, exec, s[10:11]
	s_mul_i32 s10, s18, 12
	s_sub_i32 s10, s0, s10
	s_cmp_lt_i32 s10, 4
	s_movk_i32 s11, 0x200
	s_cselect_b32 s11, s11, 0x900
	s_lshl_b32 s10, s10, 6
	s_add_i32 s10, s11, s10
	s_lshl_b32 s11, s18, 6
	s_addk_i32 s11, 0x4000
	v_add_u32_e32 v0, s11, v28
	v_ashrrev_i32_e32 v1, 31, v0
	v_lshlrev_b64 v[0:1], 11, v[0:1]
	v_lshl_add_u64 v[12:13], v[8:9], 0, v[0:1]
	v_add_u32_e32 v0, s10, v28
	v_ashrrev_i32_e32 v1, 31, v0
	s_mov_b32 s12, 0x8000
	v_lshlrev_b64 v[0:1], 11, v[0:1]
	v_add_co_u32_e32 v16, vcc, s12, v12
	v_lshl_add_u64 v[14:15], v[10:11], 0, v[0:1]
	s_nop 0
	v_addc_co_u32_e32 v17, vcc, 0, v13, vcc
	v_add_co_u32_e32 v18, vcc, s12, v14
	s_mov_b32 s12, 0x18000
	s_nop 0
	v_addc_co_u32_e32 v19, vcc, 0, v15, vcc
	v_add_co_u32_e32 v20, vcc, s82, v12
	s_waitcnt vmcnt(0) lgkmcnt(0)
	s_nop 0
	v_addc_co_u32_e32 v21, vcc, 0, v13, vcc
	v_add_co_u32_e32 v22, vcc, s82, v14
	s_barrier
	s_nop 0
	v_addc_co_u32_e32 v23, vcc, 0, v15, vcc
	v_add_co_u32_e32 v24, vcc, s12, v12
	s_nop 1
	v_addc_co_u32_e32 v25, vcc, 0, v13, vcc
	v_add_co_u32_e32 v26, vcc, s12, v14
	global_load_dwordx4 v[0:3], v[12:13], off
	global_load_dwordx4 v[4:7], v[14:15], off
	global_load_dwordx4 v[52:55], v[16:17], off
	global_load_dwordx4 v[56:59], v[18:19], off
	global_load_dwordx4 v[60:63], v[20:21], off
	global_load_dwordx4 v[64:67], v[22:23], off
	v_addc_co_u32_e32 v27, vcc, 0, v15, vcc
	global_load_dwordx4 v[68:71], v[24:25], off
	global_load_dwordx4 v[72:75], v[26:27], off
	v_add_u32_e32 v51, 0, v30
	s_barrier
	v_add_u32_e32 v181, 0, v34
	v_add_u32_e32 v183, 0, v37
	v_add_u32_e32 v185, 0, v39
	v_add_u32_e32 v187, 0, v41
	v_add_u32_e32 v189, 0, v43
	v_add_u32_e32 v191, 0, v45
	v_add_u32_e32 v193, 0, v47
	v_add_u32_e32 v180, 0, v31
	v_add_u32_e32 v182, 0, v35
	v_add_u32_e32 v184, 0, v38
	v_add_u32_e32 v186, 0, v40
	v_add_u32_e32 v188, 0, v42
	v_add_u32_e32 v190, 0, v44
	v_add_u32_e32 v192, 0, v46
	v_add_u32_e32 v194, 0, v48
	v_add_u32_e32 v195, 0, v49
	v_add_u32_e32 v196, 0, v50
	s_waitcnt vmcnt(7)
	ds_write_b128 v51, v[0:3]
	s_waitcnt vmcnt(6)
	ds_write_b128 v51, v[4:7] offset:33792
	s_waitcnt vmcnt(5)
	ds_write_b128 v51, v[52:55] offset:8448
	s_waitcnt vmcnt(4)
	ds_write_b128 v51, v[56:59] offset:42240
	s_waitcnt vmcnt(3)
	ds_write_b128 v51, v[60:63] offset:16896
	s_waitcnt vmcnt(2)
	ds_write_b128 v51, v[64:67] offset:50688
	s_waitcnt vmcnt(1)
	ds_write_b128 v51, v[68:71] offset:25344
	s_waitcnt vmcnt(0)
	ds_write_b128 v51, v[72:75] offset:59136
	global_load_dwordx4 v[52:55], v[26:27], off offset:512
	global_load_dwordx4 v[56:59], v[24:25], off offset:512
	global_load_dwordx4 v[60:63], v[22:23], off offset:512
	global_load_dwordx4 v[64:67], v[20:21], off offset:512
	global_load_dwordx4 v[68:71], v[18:19], off offset:512
	global_load_dwordx4 v[72:75], v[16:17], off offset:512
	global_load_dwordx4 v[76:79], v[14:15], off offset:512
	global_load_dwordx4 v[80:83], v[12:13], off offset:512
	s_waitcnt lgkmcnt(0)
	s_barrier
	ds_read_b128 v[0:3], v181 offset:33792
	ds_read_b128 v[4:7], v182 offset:33792
	ds_read_b128 v[84:87], v180
	ds_read_b128 v[88:91], v180 offset:64
	ds_read_b128 v[92:95], v183 offset:33792
	ds_read_b128 v[96:99], v184 offset:33792
	ds_read_b128 v[100:103], v185 offset:33792
	ds_read_b128 v[104:107], v186 offset:33792
	ds_read_b128 v[108:111], v180 offset:128
	ds_read_b128 v[112:115], v180 offset:192
	ds_read_b128 v[116:119], v187 offset:33792
	ds_read_b128 v[120:123], v188 offset:33792
	ds_read_b128 v[124:127], v189 offset:33792
	ds_read_b128 v[128:131], v190 offset:33792
	ds_read_b128 v[132:135], v180 offset:256
	ds_read_b128 v[136:139], v180 offset:320
	ds_read_b128 v[140:143], v191 offset:33792
	ds_read_b128 v[144:147], v192 offset:33792
	ds_read_b128 v[148:151], v193 offset:33792
	ds_read_b128 v[152:155], v194 offset:33792
	ds_read_b128 v[156:159], v180 offset:384
	ds_read_b128 v[160:163], v180 offset:448
	ds_read_b128 v[164:167], v195 offset:33792
	ds_read_b128 v[168:171], v196 offset:33792
	v_add_u32_e32 v197, s59, v30
	v_add_u32_e32 v198, s58, v30
	s_waitcnt vmcnt(0)
	ds_write_b128 v197, v[80:83]
	ds_write_b128 v198, v[76:79]
	ds_write_b128 v197, v[72:75] offset:8448
	ds_write_b128 v198, v[68:71] offset:8448
	ds_write_b128 v197, v[64:67] offset:16896
	ds_write_b128 v198, v[60:63] offset:16896
	ds_write_b128 v197, v[56:59] offset:25344
	ds_write_b128 v198, v[52:55] offset:25344
	global_load_dwordx4 v[52:55], v[26:27], off offset:1024
	global_load_dwordx4 v[56:59], v[24:25], off offset:1024
	global_load_dwordx4 v[60:63], v[22:23], off offset:1024
	global_load_dwordx4 v[64:67], v[20:21], off offset:1024
	global_load_dwordx4 v[68:71], v[18:19], off offset:1024
	global_load_dwordx4 v[72:75], v[16:17], off offset:1024
	global_load_dwordx4 v[76:79], v[14:15], off offset:1024
	global_load_dwordx4 v[80:83], v[12:13], off offset:1024
	s_waitcnt lgkmcnt(0)
	s_barrier
	v_mfma_f32_16x16x32_bf16 v[0:3], v[0:3], v[84:87], 0
	v_add_u32_e32 v199, s59, v31
	v_add_u32_e32 v201, s58, v34
	v_add_u32_e32 v202, s58, v35
	v_mfma_f32_16x16x32_bf16 v[4:7], v[4:7], v[84:87], 0
	v_add_u32_e32 v203, s58, v37
	v_add_u32_e32 v204, s58, v38
	v_add_u32_e32 v205, s58, v39
	v_mfma_f32_16x16x32_bf16 v[0:3], v[92:95], v[88:91], v[0:3]
	v_add_u32_e32 v206, s58, v40
	v_add_u32_e32 v207, s58, v41
	v_add_u32_e32 v208, s58, v42
	v_mfma_f32_16x16x32_bf16 v[4:7], v[96:99], v[88:91], v[4:7]
	v_add_u32_e32 v209, s58, v43
	v_add_u32_e32 v210, s58, v44
	v_add_u32_e32 v211, s58, v45
	v_mfma_f32_16x16x32_bf16 v[0:3], v[100:103], v[108:111], v[0:3]
	v_add_u32_e32 v212, s58, v46
	v_add_u32_e32 v213, s58, v47
	v_add_u32_e32 v214, s58, v48
	v_mfma_f32_16x16x32_bf16 v[4:7], v[104:107], v[108:111], v[4:7]
	ds_read_b128 v[84:87], v199
	ds_read_b128 v[88:91], v201
	ds_read_b128 v[92:95], v202
	ds_read_b128 v[96:99], v199 offset:64
	v_mfma_f32_16x16x32_bf16 v[0:3], v[116:119], v[112:115], v[0:3]
	ds_read_b128 v[100:103], v203
	ds_read_b128 v[104:107], v204
	ds_read_b128 v[108:111], v199 offset:128
	v_add_u32_e32 v215, s58, v49
	v_mfma_f32_16x16x32_bf16 v[4:7], v[120:123], v[112:115], v[4:7]
	ds_read_b128 v[112:115], v205
	ds_read_b128 v[116:119], v206
	ds_read_b128 v[120:123], v199 offset:192
	v_add_u32_e32 v218, s58, v50
	v_mfma_f32_16x16x32_bf16 v[0:3], v[124:127], v[132:135], v[0:3]
	ds_read_b128 v[124:127], v207
	v_mfma_f32_16x16x32_bf16 v[4:7], v[128:131], v[132:135], v[4:7]
	ds_read_b128 v[128:131], v208
	ds_read_b128 v[132:135], v199 offset:256
	v_mfma_f32_16x16x32_bf16 v[0:3], v[140:143], v[136:139], v[0:3]
	v_mfma_f32_16x16x32_bf16 v[4:7], v[144:147], v[136:139], v[4:7]
	ds_read_b128 v[136:139], v209
	ds_read_b128 v[140:143], v210
	ds_read_b128 v[144:147], v199 offset:320
	v_mfma_f32_16x16x32_bf16 v[0:3], v[148:151], v[156:159], v[0:3]
	ds_read_b128 v[148:151], v211
	v_mfma_f32_16x16x32_bf16 v[4:7], v[152:155], v[156:159], v[4:7]
	ds_read_b128 v[152:155], v212
	ds_read_b128 v[156:159], v199 offset:384
	v_mfma_f32_16x16x32_bf16 v[0:3], v[164:167], v[160:163], v[0:3]
	v_mfma_f32_16x16x32_bf16 v[4:7], v[168:171], v[160:163], v[4:7]
	ds_read_b128 v[160:163], v213
	ds_read_b128 v[164:167], v214
	ds_read_b128 v[168:171], v199 offset:448
	ds_read_b128 v[172:175], v215
	ds_read_b128 v[176:179], v218
	s_waitcnt vmcnt(0)
	ds_write_b128 v51, v[80:83]
	ds_write_b128 v51, v[76:79] offset:33792
	ds_write_b128 v51, v[72:75] offset:8448
	ds_write_b128 v51, v[68:71] offset:42240
	ds_write_b128 v51, v[64:67] offset:16896
	ds_write_b128 v51, v[60:63] offset:50688
	ds_write_b128 v51, v[56:59] offset:25344
	ds_write_b128 v51, v[52:55] offset:59136
	global_load_dwordx4 v[52:55], v[26:27], off offset:1536
	s_nop 0
	global_load_dwordx4 v[24:27], v[24:25], off offset:1536
	s_nop 0
	global_load_dwordx4 v[56:59], v[22:23], off offset:1536
	s_nop 0
	global_load_dwordx4 v[20:23], v[20:21], off offset:1536
	s_nop 0
	global_load_dwordx4 v[60:63], v[18:19], off offset:1536
	s_nop 0
	global_load_dwordx4 v[16:19], v[16:17], off offset:1536
	s_nop 0
	global_load_dwordx4 v[64:67], v[14:15], off offset:1536
	s_nop 0
	global_load_dwordx4 v[12:15], v[12:13], off offset:1536
	s_waitcnt lgkmcnt(0)
	s_barrier
	v_mfma_f32_16x16x32_bf16 v[0:3], v[88:91], v[84:87], v[0:3]
	ds_read_b128 v[68:71], v181 offset:33792
	ds_read_b128 v[72:75], v182 offset:33792
	ds_read_b128 v[76:79], v180
	ds_read_b128 v[80:83], v180 offset:64
	v_mfma_f32_16x16x32_bf16 v[4:7], v[92:95], v[84:87], v[4:7]
	v_mfma_f32_16x16x32_bf16 v[0:3], v[100:103], v[96:99], v[0:3]
	v_mfma_f32_16x16x32_bf16 v[4:7], v[104:107], v[96:99], v[4:7]
	ds_read_b128 v[84:87], v183 offset:33792
	ds_read_b128 v[88:91], v184 offset:33792
	ds_read_b128 v[92:95], v185 offset:33792
	ds_read_b128 v[96:99], v186 offset:33792
	v_mfma_f32_16x16x32_bf16 v[0:3], v[112:115], v[108:111], v[0:3]
	v_mfma_f32_16x16x32_bf16 v[4:7], v[116:119], v[108:111], v[4:7]
	ds_read_b128 v[100:103], v180 offset:128
	ds_read_b128 v[104:107], v180 offset:192
	ds_read_b128 v[108:111], v187 offset:33792
	ds_read_b128 v[112:115], v188 offset:33792
	v_mfma_f32_16x16x32_bf16 v[0:3], v[124:127], v[120:123], v[0:3]
	v_mfma_f32_16x16x32_bf16 v[4:7], v[128:131], v[120:123], v[4:7]
	ds_read_b128 v[116:119], v189 offset:33792
	ds_read_b128 v[120:123], v190 offset:33792
	ds_read_b128 v[124:127], v180 offset:256
	ds_read_b128 v[128:131], v180 offset:320
	v_mfma_f32_16x16x32_bf16 v[0:3], v[136:139], v[132:135], v[0:3]
	v_mfma_f32_16x16x32_bf16 v[4:7], v[140:143], v[132:135], v[4:7]
	v_mfma_f32_16x16x32_bf16 v[0:3], v[148:151], v[144:147], v[0:3]
	v_mfma_f32_16x16x32_bf16 v[4:7], v[152:155], v[144:147], v[4:7]
	ds_read_b128 v[132:135], v191 offset:33792
	ds_read_b128 v[136:139], v192 offset:33792
	ds_read_b128 v[140:143], v193 offset:33792
	ds_read_b128 v[144:147], v194 offset:33792
	v_mfma_f32_16x16x32_bf16 v[0:3], v[160:163], v[156:159], v[0:3]
	v_mfma_f32_16x16x32_bf16 v[4:7], v[164:167], v[156:159], v[4:7]
	ds_read_b128 v[148:151], v180 offset:384
	ds_read_b128 v[152:155], v180 offset:448
	ds_read_b128 v[156:159], v195 offset:33792
	ds_read_b128 v[160:163], v196 offset:33792
	v_mfma_f32_16x16x32_bf16 v[0:3], v[172:175], v[168:171], v[0:3]
	v_mfma_f32_16x16x32_bf16 v[4:7], v[176:179], v[168:171], v[4:7]
	s_waitcnt lgkmcnt(14)
	v_mfma_f32_16x16x32_bf16 v[0:3], v[68:71], v[76:79], v[0:3]
	s_waitcnt vmcnt(0)
	ds_write_b128 v197, v[12:15]
	ds_write_b128 v198, v[64:67]
	ds_write_b128 v197, v[16:19] offset:8448
	ds_write_b128 v198, v[60:63] offset:8448
	ds_write_b128 v197, v[20:23] offset:16896
	ds_write_b128 v198, v[56:59] offset:16896
	ds_write_b128 v197, v[24:27] offset:25344
	ds_write_b128 v198, v[52:55] offset:25344
	v_mfma_f32_16x16x32_bf16 v[4:7], v[72:75], v[76:79], v[4:7]
	s_waitcnt lgkmcnt(0)
	s_barrier
	v_mfma_f32_16x16x32_bf16 v[0:3], v[84:87], v[80:83], v[0:3]
	ds_read_b128 v[12:15], v201
	ds_read_b128 v[16:19], v202
	ds_read_b128 v[20:23], v199
	ds_read_b128 v[24:27], v199 offset:64
	ds_read_b128 v[52:55], v203
	ds_read_b128 v[56:59], v204
	ds_read_b128 v[60:63], v205
	ds_read_b128 v[64:67], v206
	v_mfma_f32_16x16x32_bf16 v[4:7], v[88:91], v[80:83], v[4:7]
	ds_read_b128 v[68:71], v199 offset:128
	ds_read_b128 v[72:75], v199 offset:192
	ds_read_b128 v[76:79], v207
	ds_read_b128 v[80:83], v208
	v_mfma_f32_16x16x32_bf16 v[0:3], v[92:95], v[100:103], v[0:3]
	v_mfma_f32_16x16x32_bf16 v[4:7], v[96:99], v[100:103], v[4:7]
	ds_read_b128 v[84:87], v209
	ds_read_b128 v[88:91], v210
	ds_read_b128 v[92:95], v199 offset:256
	ds_read_b128 v[96:99], v199 offset:320
	v_mfma_f32_16x16x32_bf16 v[0:3], v[108:111], v[104:107], v[0:3]
	v_mfma_f32_16x16x32_bf16 v[4:7], v[112:115], v[104:107], v[4:7]
	ds_read_b128 v[100:103], v211
	ds_read_b128 v[104:107], v212
	ds_read_b128 v[108:111], v213
	ds_read_b128 v[112:115], v214
	v_mfma_f32_16x16x32_bf16 v[0:3], v[116:119], v[124:127], v[0:3]
	v_mfma_f32_16x16x32_bf16 v[4:7], v[120:123], v[124:127], v[4:7]
	v_mfma_f32_16x16x32_bf16 v[0:3], v[132:135], v[128:131], v[0:3]
	v_mfma_f32_16x16x32_bf16 v[4:7], v[136:139], v[128:131], v[4:7]
	ds_read_b128 v[116:119], v199 offset:384
	ds_read_b128 v[120:123], v199 offset:448
	ds_read_b128 v[124:127], v215
	ds_read_b128 v[128:131], v218
	v_mfma_f32_16x16x32_bf16 v[0:3], v[140:143], v[148:151], v[0:3]
	v_mfma_f32_16x16x32_bf16 v[4:7], v[144:147], v[148:151], v[4:7]
	v_mfma_f32_16x16x32_bf16 v[0:3], v[156:159], v[152:155], v[0:3]
	v_mfma_f32_16x16x32_bf16 v[4:7], v[160:163], v[152:155], v[4:7]
	s_waitcnt lgkmcnt(14)
	v_mfma_f32_16x16x32_bf16 v[0:3], v[12:15], v[20:23], v[0:3]
	v_or_b32_e32 v12, s11, v29
	s_and_b32 s11, s10, 0xffffff00
	v_ashrrev_i32_e32 v13, 31, v12
	v_mfma_f32_16x16x32_bf16 v[0:3], v[52:55], v[24:27], v[0:3]
	s_cmpk_eq_i32 s11, 0xa00
	s_cselect_b64 vcc, -1, 0
	v_lshlrev_b64 v[12:13], 13, v[12:13]
	v_mfma_f32_16x16x32_bf16 v[4:7], v[16:19], v[20:23], v[4:7]
	v_cndmask_b32_e32 v14, 1.0, v224, vcc
	v_lshl_add_u64 v[12:13], s[24:25], 0, v[12:13]
	s_ashr_i32 s11, s10, 31
	v_mfma_f32_16x16x32_bf16 v[0:3], v[60:63], v[68:71], v[0:3]
	v_lshl_add_u64 v[12:13], s[10:11], 1, v[12:13]
	v_lshl_add_u64 v[12:13], s[8:9], 1, v[12:13]
	v_lshl_add_u64 v[12:13], v[12:13], 0, v[32:33]
	v_mfma_f32_16x16x32_bf16 v[4:7], v[56:59], v[24:27], v[4:7]
	s_add_i32 s0, s0, s5
	s_cmpk_lt_i32 s0, 0xc0
	s_waitcnt lgkmcnt(13)
	v_mfma_f32_16x16x32_bf16 v[0:3], v[76:79], v[72:75], v[0:3]
	v_mfma_f32_16x16x32_bf16 v[4:7], v[64:67], v[68:71], v[4:7]
	s_waitcnt lgkmcnt(9)
	v_mfma_f32_16x16x32_bf16 v[0:3], v[84:87], v[92:95], v[0:3]
	v_mfma_f32_16x16x32_bf16 v[4:7], v[80:83], v[72:75], v[4:7]
	s_waitcnt lgkmcnt(7)
	v_mfma_f32_16x16x32_bf16 v[0:3], v[100:103], v[96:99], v[0:3]
	v_mfma_f32_16x16x32_bf16 v[4:7], v[88:91], v[92:95], v[4:7]
	s_waitcnt lgkmcnt(3)
	v_mfma_f32_16x16x32_bf16 v[0:3], v[108:111], v[116:119], v[0:3]
	v_mfma_f32_16x16x32_bf16 v[4:7], v[104:107], v[96:99], v[4:7]
	s_waitcnt lgkmcnt(1)
	v_mfma_f32_16x16x32_bf16 v[0:3], v[124:127], v[120:123], v[0:3]
	v_mfma_f32_16x16x32_bf16 v[4:7], v[112:115], v[116:119], v[4:7]
	s_nop 6
	v_mul_f32_e32 v0, v14, v0
	v_mul_f32_e32 v1, v14, v1
	v_cvt_pk_bf16_f32 v0, v0, v1
	v_mul_f32_e32 v1, v14, v2
	v_mul_f32_e32 v2, v14, v3
	v_cvt_pk_bf16_f32 v1, v1, v2
	global_store_dwordx2 v[12:13], v[0:1], off
	s_waitcnt lgkmcnt(0)
	v_mfma_f32_16x16x32_bf16 v[0:3], v[128:131], v[120:123], v[4:7]
	s_nop 7
	v_mul_f32_e32 v0, v14, v0
	v_mul_f32_e32 v1, v14, v1
	v_cvt_pk_bf16_f32 v0, v0, v1
	v_mul_f32_e32 v1, v14, v2
	v_mul_f32_e32 v2, v14, v3
	v_cvt_pk_bf16_f32 v1, v1, v2
	global_store_dwordx2 v[12:13], v[0:1], off offset:32
	s_cbranch_scc0 .LBB0_557

.LBB0_1474:
	s_and_b32 s12, s27, 0xffffffc0
	s_add_i32 s13, s12, 0x4000
	v_add_u32_e32 v0, s13, v15
	s_and_b32 s12, s28, 0x3c0
	v_mad_i64_i32 v[22:23], s[18:19], v0, s44, v[8:9]
	v_add_u32_e32 v0, s12, v15
	v_add_co_u32_e32 v26, vcc, 0xa000, v22
	v_mad_i64_i32 v[24:25], s[18:19], v0, s44, v[10:11]
	s_nop 0
	v_addc_co_u32_e32 v27, vcc, 0, v23, vcc
	v_add_co_u32_e32 v28, vcc, 0xa000, v24
	s_mov_b32 s18, 0x14000
	s_nop 0
	v_addc_co_u32_e32 v29, vcc, 0, v25, vcc
	v_add_co_u32_e32 v30, vcc, s18, v22
	global_load_dwordx4 v[0:3], v[22:23], off
	global_load_dwordx4 v[4:7], v[24:25], off
	v_addc_co_u32_e32 v31, vcc, 0, v23, vcc
	v_add_co_u32_e32 v34, vcc, s18, v24
	global_load_dwordx4 v[62:65], v[26:27], off
	global_load_dwordx4 v[66:69], v[28:29], off
	v_addc_co_u32_e32 v35, vcc, 0, v25, vcc
	v_add_co_u32_e32 v38, vcc, 0x1e000, v22
	global_load_dwordx4 v[70:73], v[30:31], off
	global_load_dwordx4 v[74:77], v[34:35], off
	v_addc_co_u32_e32 v39, vcc, 0, v23, vcc
	v_add_co_u32_e32 v40, vcc, 0x1e000, v24
	s_ashr_i32 s18, s13, 8
	s_nop 0
	v_addc_co_u32_e32 v41, vcc, 0, v25, vcc
	global_load_dwordx4 v[84:87], v[38:39], off
	global_load_dwordx4 v[88:91], v[40:41], off
	s_ashr_i32 s19, s18, 31
	s_lshl_b64 s[18:19], s[18:19], 20
	s_add_u32 s18, s40, s18
	s_addc_u32 s19, s41, s19
	s_and_b32 s30, s26, 0x8000
	s_add_u32 s18, s18, s30
	s_addc_u32 s19, s19, 0
	s_lshr_b32 s30, s27, 5
	s_and_b32 s30, s30, 4
	s_or_b32 s30, s30, s0
	v_or_b32_e32 v32, s12, v14
	s_lshl_b32 s30, s30, 10
	v_add_u32_e32 v37, s10, v32
	s_add_u32 s18, s18, s30
	v_ashrrev_i32_e32 v78, 8, v37
	s_addc_u32 s19, s19, 0
	v_ashrrev_i32_e32 v79, 31, v78
	v_lshl_add_u64 v[20:21], s[18:19], 0, v[12:13]
	v_lshlrev_b64 v[78:79], 18, v[78:79]
	v_lshlrev_b32_e32 v32, 8, v37
	v_lshl_add_u64 v[20:21], v[20:21], 0, v[78:79]
	v_and_b32_e32 v32, 0x6000, v32
	v_lshl_add_u64 v[20:21], v[20:21], 0, v[32:33]
	v_lshrrev_b32_e32 v32, 4, v37
	v_lshl_add_u64 v[20:21], v[20:21], 0, v[16:17]
	v_and_b32_e32 v32, 8, v32
	v_lshl_add_u64 v[20:21], v[20:21], 0, v[32:33]
	v_lshl_add_u64 v[20:21], v[20:21], 0, v[18:19]
	v_add_co_u32_e32 v78, vcc, s82, v20
	s_mov_b32 s18, 0x30000
	s_nop 0
	v_addc_co_u32_e32 v79, vcc, 0, v21, vcc
	v_add_co_u32_e32 v92, vcc, s51, v20
	v_add_u32_e32 v61, 0, v43
	s_nop 0
	v_addc_co_u32_e32 v93, vcc, 0, v21, vcc
	v_add_co_u32_e32 v94, vcc, s18, v20
	v_add_u32_e32 v37, 0, v44
	s_nop 0
	v_addc_co_u32_e32 v95, vcc, 0, v21, vcc
	global_load_dword v82, v[20:21], off
	global_load_dword v83, v[78:79], off
	global_load_dword v81, v[78:79], off offset:512
	global_load_dword v80, v[20:21], off offset:512
	s_nop 0
	global_load_dword v79, v[92:93], off
	global_load_dword v78, v[92:93], off offset:512
	global_load_dword v21, v[94:95], off
	global_load_dword v32, v[94:95], off offset:512
	s_barrier
	v_or_b32_e32 v20, s13, v42
	s_waitcnt vmcnt(15)
	ds_write_b128 v61, v[0:3]
	s_waitcnt vmcnt(14)
	ds_write_b128 v61, v[4:7] offset:33792
	s_waitcnt vmcnt(13)
	ds_write_b128 v61, v[62:65] offset:8448
	s_waitcnt vmcnt(12)
	ds_write_b128 v61, v[66:69] offset:42240
	s_waitcnt vmcnt(11)
	ds_write_b128 v61, v[70:73] offset:16896
	s_waitcnt vmcnt(10)
	ds_write_b128 v61, v[74:77] offset:50688
	s_waitcnt vmcnt(9)
	ds_write_b128 v61, v[84:87] offset:25344
	s_waitcnt vmcnt(8)
	ds_write_b128 v61, v[88:91] offset:59136
	global_load_dwordx4 v[84:87], v[22:23], off offset:512
	global_load_dwordx4 v[88:91], v[24:25], off offset:512
	global_load_dwordx4 v[92:95], v[26:27], off offset:512
	global_load_dwordx4 v[96:99], v[28:29], off offset:512
	global_load_dwordx4 v[100:103], v[30:31], off offset:512
	global_load_dwordx4 v[104:107], v[34:35], off offset:512
	global_load_dwordx4 v[108:111], v[38:39], off offset:512
	global_load_dwordx4 v[112:115], v[40:41], off offset:512
	s_waitcnt lgkmcnt(0)
	s_barrier
	v_add_u32_e32 v62, 0, v45
	v_add_u32_e32 v63, 0, v47
	v_add_u32_e32 v66, 0, v49
	v_add_u32_e32 v67, 0, v51
	v_add_u32_e32 v70, 0, v53
	v_add_u32_e32 v72, 0, v55
	v_add_u32_e32 v74, 0, v57
	v_add_u32_e32 v64, 0, v46
	ds_read_b128 v[0:3], v62 offset:33792
	ds_read_b128 v[4:7], v64 offset:33792
	ds_read_b128 v[116:119], v37
	ds_read_b128 v[120:123], v37 offset:64
	v_add_u32_e32 v65, 0, v48
	ds_read_b128 v[124:127], v63 offset:33792
	ds_read_b128 v[128:131], v65 offset:33792
	v_add_u32_e32 v68, 0, v50
	ds_read_b128 v[132:135], v66 offset:33792
	ds_read_b128 v[136:139], v68 offset:33792
	ds_read_b128 v[140:143], v37 offset:128
	ds_read_b128 v[144:147], v37 offset:192
	v_add_u32_e32 v69, 0, v52
	ds_read_b128 v[148:151], v67 offset:33792
	ds_read_b128 v[152:155], v69 offset:33792
	v_add_u32_e32 v71, 0, v54
	ds_read_b128 v[156:159], v70 offset:33792
	ds_read_b128 v[160:163], v71 offset:33792
	ds_read_b128 v[164:167], v37 offset:256
	ds_read_b128 v[168:171], v37 offset:320
	v_add_u32_e32 v73, 0, v56
	ds_read_b128 v[172:175], v72 offset:33792
	ds_read_b128 v[176:179], v73 offset:33792
	v_add_u32_e32 v75, 0, v58
	ds_read_b128 v[180:183], v74 offset:33792
	ds_read_b128 v[184:187], v75 offset:33792
	ds_read_b128 v[188:191], v37 offset:384
	ds_read_b128 v[192:195], v37 offset:448
	v_add_u32_e32 v76, 0, v59
	v_add_u32_e32 v77, 0, v60
	ds_read_b128 v[196:199], v76 offset:33792
	ds_read_b128 v[202:205], v77 offset:33792
	v_add_u32_e32 v201, s59, v43
	v_add_u32_e32 v230, s58, v43
	s_waitcnt vmcnt(7)
	ds_write_b128 v201, v[84:87]
	s_waitcnt vmcnt(6)
	ds_write_b128 v230, v[88:91]
	s_waitcnt vmcnt(5)
	ds_write_b128 v201, v[92:95] offset:8448
	s_waitcnt vmcnt(4)
	ds_write_b128 v230, v[96:99] offset:8448
	s_waitcnt vmcnt(3)
	ds_write_b128 v201, v[100:103] offset:16896
	s_waitcnt vmcnt(2)
	ds_write_b128 v230, v[104:107] offset:16896
	s_waitcnt vmcnt(1)
	ds_write_b128 v201, v[108:111] offset:25344
	s_waitcnt vmcnt(0)
	ds_write_b128 v230, v[112:115] offset:25344
	global_load_dwordx4 v[84:87], v[22:23], off offset:1024
	global_load_dwordx4 v[88:91], v[24:25], off offset:1024
	global_load_dwordx4 v[92:95], v[26:27], off offset:1024
	global_load_dwordx4 v[96:99], v[28:29], off offset:1024
	global_load_dwordx4 v[100:103], v[30:31], off offset:1024
	global_load_dwordx4 v[104:107], v[34:35], off offset:1024
	global_load_dwordx4 v[108:111], v[38:39], off offset:1024
	global_load_dwordx4 v[112:115], v[40:41], off offset:1024
	s_waitcnt lgkmcnt(0)
	s_barrier
	v_mfma_f32_16x16x32_bf16 v[0:3], v[0:3], v[116:119], 0
	v_add_u32_e32 v231, s59, v44
	v_add_u32_e32 v232, s58, v45
	v_add_u32_e32 v233, s58, v46
	v_mfma_f32_16x16x32_bf16 v[4:7], v[4:7], v[116:119], 0
	v_add_u32_e32 v234, s58, v47
	v_add_u32_e32 v235, s58, v48
	v_add_u32_e32 v236, s58, v49
	v_mfma_f32_16x16x32_bf16 v[0:3], v[124:127], v[120:123], v[0:3]
	v_add_u32_e32 v237, s58, v50
	v_add_u32_e32 v243, s58, v51
	v_add_u32_e32 v244, s58, v52
	v_mfma_f32_16x16x32_bf16 v[4:7], v[128:131], v[120:123], v[4:7]
	v_add_u32_e32 v245, s58, v53
	v_add_u32_e32 v246, s58, v54
	v_add_u32_e32 v247, s58, v55
	v_mfma_f32_16x16x32_bf16 v[0:3], v[132:135], v[140:143], v[0:3]
	v_add_u32_e32 v248, s58, v56
	v_add_u32_e32 v249, s58, v57
	v_add_u32_e32 v250, s58, v58
	v_mfma_f32_16x16x32_bf16 v[4:7], v[136:139], v[140:143], v[4:7]
	ds_read_b128 v[116:119], v231
	ds_read_b128 v[120:123], v232
	ds_read_b128 v[124:127], v233
	ds_read_b128 v[128:131], v231 offset:64
	v_mfma_f32_16x16x32_bf16 v[0:3], v[148:151], v[144:147], v[0:3]
	ds_read_b128 v[132:135], v234
	ds_read_b128 v[136:139], v235
	ds_read_b128 v[140:143], v231 offset:128
	v_add_u32_e32 v251, s58, v59
	v_mfma_f32_16x16x32_bf16 v[4:7], v[152:155], v[144:147], v[4:7]
	ds_read_b128 v[144:147], v236
	ds_read_b128 v[148:151], v237
	ds_read_b128 v[152:155], v231 offset:192
	v_add_u32_e32 v225, s58, v60
	v_mfma_f32_16x16x32_bf16 v[0:3], v[156:159], v[164:167], v[0:3]
	ds_read_b128 v[156:159], v243
	v_mfma_f32_16x16x32_bf16 v[4:7], v[160:163], v[164:167], v[4:7]
	ds_read_b128 v[160:163], v244
	ds_read_b128 v[164:167], v231 offset:256
	v_mfma_f32_16x16x32_bf16 v[0:3], v[172:175], v[168:171], v[0:3]
	v_mfma_f32_16x16x32_bf16 v[4:7], v[176:179], v[168:171], v[4:7]
	ds_read_b128 v[168:171], v245
	ds_read_b128 v[172:175], v246
	ds_read_b128 v[176:179], v231 offset:320
	v_mfma_f32_16x16x32_bf16 v[0:3], v[180:183], v[188:191], v[0:3]
	ds_read_b128 v[180:183], v247
	v_mfma_f32_16x16x32_bf16 v[4:7], v[184:187], v[188:191], v[4:7]
	ds_read_b128 v[184:187], v248
	ds_read_b128 v[188:191], v231 offset:384
	v_mfma_f32_16x16x32_bf16 v[0:3], v[196:199], v[192:195], v[0:3]
	v_mfma_f32_16x16x32_bf16 v[4:7], v[202:205], v[192:195], v[4:7]
	ds_read_b128 v[192:195], v249
	ds_read_b128 v[196:199], v250
	ds_read_b128 v[202:205], v231 offset:448
	ds_read_b128 v[206:209], v251
	ds_read_b128 v[210:213], v225
	s_waitcnt lgkmcnt(14)
	v_mfma_f32_16x16x32_bf16 v[0:3], v[120:123], v[116:119], v[0:3]
	s_waitcnt vmcnt(7)
	ds_write_b128 v61, v[84:87]
	s_waitcnt vmcnt(6)
	ds_write_b128 v61, v[88:91] offset:33792
	s_waitcnt vmcnt(5)
	ds_write_b128 v61, v[92:95] offset:8448
	s_waitcnt vmcnt(4)
	ds_write_b128 v61, v[96:99] offset:42240
	s_waitcnt vmcnt(3)
	ds_write_b128 v61, v[100:103] offset:16896
	s_waitcnt vmcnt(2)
	ds_write_b128 v61, v[104:107] offset:50688
	s_waitcnt vmcnt(1)
	ds_write_b128 v61, v[108:111] offset:25344
	s_waitcnt vmcnt(0)
	ds_write_b128 v61, v[112:115] offset:59136
	s_waitcnt lgkmcnt(0)
	s_barrier
	v_mfma_f32_16x16x32_bf16 v[4:7], v[124:127], v[116:119], v[4:7]
	v_mfma_f32_16x16x32_bf16 v[0:3], v[132:135], v[128:131], v[0:3]
	v_mfma_f32_16x16x32_bf16 v[4:7], v[136:139], v[128:131], v[4:7]
	v_mfma_f32_16x16x32_bf16 v[0:3], v[144:147], v[140:143], v[0:3]
	v_mfma_f32_16x16x32_bf16 v[4:7], v[148:151], v[140:143], v[4:7]
	v_mfma_f32_16x16x32_bf16 v[0:3], v[156:159], v[152:155], v[0:3]
	v_mfma_f32_16x16x32_bf16 v[4:7], v[160:163], v[152:155], v[4:7]
	v_mfma_f32_16x16x32_bf16 v[0:3], v[168:171], v[164:167], v[0:3]
	v_mfma_f32_16x16x32_bf16 v[4:7], v[172:175], v[164:167], v[4:7]
	v_mfma_f32_16x16x32_bf16 v[0:3], v[180:183], v[176:179], v[0:3]
	v_mfma_f32_16x16x32_bf16 v[4:7], v[184:187], v[176:179], v[4:7]
	v_mfma_f32_16x16x32_bf16 v[0:3], v[192:195], v[188:191], v[0:3]
	v_mfma_f32_16x16x32_bf16 v[4:7], v[196:199], v[188:191], v[4:7]
	v_mfma_f32_16x16x32_bf16 v[116:119], v[206:209], v[202:205], v[0:3]
	v_mfma_f32_16x16x32_bf16 v[0:3], v[210:213], v[202:205], v[4:7]
	s_nop 5
	global_load_dwordx4 v[4:7], v[22:23], off offset:1536
	global_load_dwordx4 v[84:87], v[24:25], off offset:1536
	global_load_dwordx4 v[88:91], v[26:27], off offset:1536
	global_load_dwordx4 v[92:95], v[28:29], off offset:1536
	global_load_dwordx4 v[96:99], v[30:31], off offset:1536
	global_load_dwordx4 v[100:103], v[34:35], off offset:1536
	global_load_dwordx4 v[104:107], v[38:39], off offset:1536
	global_load_dwordx4 v[108:111], v[40:41], off offset:1536
	ds_read_b128 v[112:115], v37
	ds_read_b128 v[120:123], v62 offset:33792
	ds_read_b128 v[124:127], v64 offset:33792
	ds_read_b128 v[128:131], v37 offset:64
	ds_read_b128 v[132:135], v63 offset:33792
	ds_read_b128 v[136:139], v65 offset:33792
	ds_read_b128 v[140:143], v37 offset:128
	ds_read_b128 v[144:147], v66 offset:33792
	ds_read_b128 v[148:151], v68 offset:33792
	ds_read_b128 v[152:155], v37 offset:192
	ds_read_b128 v[156:159], v67 offset:33792
	ds_read_b128 v[160:163], v69 offset:33792
	ds_read_b128 v[164:167], v37 offset:256
	ds_read_b128 v[168:171], v70 offset:33792
	ds_read_b128 v[172:175], v71 offset:33792
	ds_read_b128 v[176:179], v37 offset:320
	ds_read_b128 v[180:183], v72 offset:33792
	ds_read_b128 v[184:187], v73 offset:33792
	ds_read_b128 v[188:191], v37 offset:384
	ds_read_b128 v[192:195], v74 offset:33792
	ds_read_b128 v[196:199], v75 offset:33792
	ds_read_b128 v[202:205], v37 offset:448
	ds_read_b128 v[206:209], v76 offset:33792
	ds_read_b128 v[210:213], v77 offset:33792
	v_cvt_f32_ubyte1_e32 v215, v83
	v_cvt_f32_ubyte0_e32 v214, v83
	v_cvt_f32_ubyte3_e32 v221, v83
	v_cvt_f32_ubyte2_e32 v220, v83
	v_rcp_iflag_f32_e32 v218, v214
	v_rcp_iflag_f32_e32 v219, v215
	v_rcp_iflag_f32_e32 v222, v220
	v_rcp_iflag_f32_e32 v223, v221
	s_waitcnt vmcnt(7)
	ds_write_b128 v201, v[4:7]
	s_waitcnt vmcnt(6)
	ds_write_b128 v230, v[84:87]
	s_waitcnt vmcnt(5)
	ds_write_b128 v201, v[88:91] offset:8448
	s_waitcnt vmcnt(4)
	ds_write_b128 v230, v[92:95] offset:8448
	s_waitcnt vmcnt(3)
	ds_write_b128 v201, v[96:99] offset:16896
	s_waitcnt vmcnt(2)
	ds_write_b128 v230, v[100:103] offset:16896
	s_waitcnt vmcnt(1)
	ds_write_b128 v201, v[104:107] offset:25344
	s_waitcnt vmcnt(0)
	ds_write_b128 v230, v[108:111] offset:25344
	global_load_dwordx4 v[4:7], v[22:23], off offset:2048
	s_nop 0
	global_load_dwordx4 v[22:25], v[24:25], off offset:2048
	s_nop 0
	global_load_dwordx4 v[84:87], v[26:27], off offset:2048
	s_nop 0
	global_load_dwordx4 v[26:29], v[28:29], off offset:2048
	s_nop 0
	global_load_dwordx4 v[88:91], v[30:31], off offset:2048
	global_load_dwordx4 v[92:95], v[34:35], off offset:2048
	global_load_dwordx4 v[96:99], v[38:39], off offset:2048
	s_nop 0
	global_load_dwordx4 v[38:41], v[40:41], off offset:2048
	s_waitcnt lgkmcnt(0)
	s_barrier
	v_cvt_f32_ubyte1_e32 v229, v82
	v_cvt_f32_ubyte0_e32 v228, v82
	v_cvt_f32_ubyte3_e32 v83, v82
	v_cvt_f32_ubyte2_e32 v82, v82
	v_pk_mul_f32 v[82:83], v[222:223], v[82:83]
	v_pk_mul_f32 v[218:219], v[218:219], v[228:229]
	v_pk_mul_f32 v[118:119], v[82:83], v[118:119]
	v_pk_mul_f32 v[116:117], v[218:219], v[116:117]
	v_cvt_f32_ubyte1_e32 v219, v81
	v_cvt_f32_ubyte0_e32 v218, v81
	v_mfma_f32_16x16x32_bf16 v[116:119], v[120:123], v[112:115], v[116:119]
	v_cvt_f32_ubyte3_e32 v223, v81
	v_cvt_f32_ubyte2_e32 v222, v81
	v_cvt_f32_ubyte1_e32 v121, v80
	v_mfma_f32_16x16x32_bf16 v[116:119], v[132:135], v[128:131], v[116:119]
	v_rcp_iflag_f32_e32 v132, v218
	v_rcp_iflag_f32_e32 v134, v222
	v_rcp_iflag_f32_e32 v135, v223
	v_mfma_f32_16x16x32_bf16 v[116:119], v[144:147], v[140:143], v[116:119]
	v_rcp_iflag_f32_e32 v133, v219
	v_cvt_f32_ubyte0_e32 v120, v80
	v_cvt_f32_ubyte3_e32 v123, v80
	v_mfma_f32_16x16x32_bf16 v[116:119], v[156:159], v[152:155], v[116:119]
	v_cvt_f32_ubyte2_e32 v122, v80
	v_mfma_f32_16x16x32_bf16 v[116:119], v[168:171], v[164:167], v[116:119]
	v_mfma_f32_16x16x32_bf16 v[116:119], v[180:183], v[176:179], v[116:119]
	v_mfma_f32_16x16x32_bf16 v[116:119], v[192:195], v[188:191], v[116:119]
	v_mfma_f32_16x16x32_bf16 v[80:83], v[206:209], v[202:205], v[116:119]
	s_nop 6
	v_mul_f32_e64 v116, v134, v122
	v_mul_f32_e64 v117, v135, v123
	v_pk_mul_f32 v[118:119], v[132:133], v[120:121]
	v_pk_mul_f32 v[2:3], v[116:117], v[2:3]
	v_pk_mul_f32 v[0:1], v[118:119], v[0:1]
	s_nop 1
	v_mfma_f32_16x16x32_bf16 v[0:3], v[124:127], v[112:115], v[0:3]
	v_mfma_f32_16x16x32_bf16 v[0:3], v[136:139], v[128:131], v[0:3]
	v_mfma_f32_16x16x32_bf16 v[0:3], v[148:151], v[140:143], v[0:3]
	v_mfma_f32_16x16x32_bf16 v[0:3], v[160:163], v[152:155], v[0:3]
	v_mfma_f32_16x16x32_bf16 v[0:3], v[172:175], v[164:167], v[0:3]
	v_mfma_f32_16x16x32_bf16 v[0:3], v[184:187], v[176:179], v[0:3]
	v_mfma_f32_16x16x32_bf16 v[0:3], v[196:199], v[188:191], v[0:3]
	ds_read_b128 v[100:103], v232
	ds_read_b128 v[104:107], v233
	ds_read_b128 v[108:111], v231
	ds_read_b128 v[112:115], v231 offset:64
	ds_read_b128 v[116:119], v234
	ds_read_b128 v[120:123], v235
	ds_read_b128 v[124:127], v236
	ds_read_b128 v[128:131], v237
	ds_read_b128 v[132:135], v231 offset:128
	ds_read_b128 v[136:139], v231 offset:192
	ds_read_b128 v[140:143], v243
	ds_read_b128 v[144:147], v244
	ds_read_b128 v[148:151], v245
	ds_read_b128 v[152:155], v246
	ds_read_b128 v[156:159], v231 offset:256
	ds_read_b128 v[160:163], v231 offset:320
	ds_read_b128 v[164:167], v247
	ds_read_b128 v[168:171], v248
	ds_read_b128 v[172:175], v249
	ds_read_b128 v[176:179], v250
	ds_read_b128 v[180:183], v231 offset:384
	ds_read_b128 v[184:187], v231 offset:448
	ds_read_b128 v[188:191], v251
	ds_read_b128 v[192:195], v225
	v_mfma_f32_16x16x32_bf16 v[0:3], v[210:213], v[202:205], v[0:3]
	v_cvt_f32_ubyte1_e32 v31, v79
	v_cvt_f32_ubyte0_e32 v30, v79
	v_cvt_f32_ubyte3_e32 v197, v79
	v_cvt_f32_ubyte2_e32 v196, v79
	v_rcp_iflag_f32_e32 v34, v30
	v_rcp_iflag_f32_e32 v35, v31
	v_rcp_iflag_f32_e32 v198, v196
	v_rcp_iflag_f32_e32 v199, v197
	s_waitcnt vmcnt(7)
	ds_write_b128 v61, v[4:7]
	s_waitcnt vmcnt(6)
	ds_write_b128 v61, v[22:25] offset:33792
	v_pk_mul_f32 v[34:35], v[34:35], v[214:215]
	s_waitcnt vmcnt(5)
	ds_write_b128 v61, v[84:87] offset:8448
	s_waitcnt vmcnt(4)
	ds_write_b128 v61, v[26:29] offset:42240
	s_waitcnt vmcnt(3)
	ds_write_b128 v61, v[88:91] offset:16896
	v_pk_mul_f32 v[198:199], v[198:199], v[220:221]
	v_pk_mul_f32 v[80:81], v[34:35], v[80:81]
	v_pk_mul_f32 v[82:83], v[198:199], v[82:83]
	v_cvt_f32_ubyte1_e32 v35, v78
	v_cvt_f32_ubyte0_e32 v34, v78
	s_waitcnt lgkmcnt(14)
	v_mfma_f32_16x16x32_bf16 v[80:83], v[100:103], v[108:111], v[80:83]
	v_cvt_f32_ubyte3_e32 v199, v78
	v_cvt_f32_ubyte2_e32 v198, v78
	v_rcp_iflag_f32_e32 v100, v198
	v_mfma_f32_16x16x32_bf16 v[80:83], v[116:119], v[112:115], v[80:83]
	v_rcp_iflag_f32_e32 v101, v199
	s_waitcnt vmcnt(2)
	ds_write_b128 v61, v[92:95] offset:50688
	s_waitcnt vmcnt(1)
	ds_write_b128 v61, v[96:99] offset:25344
	s_waitcnt vmcnt(0)
	ds_write_b128 v61, v[38:41] offset:59136
	s_waitcnt lgkmcnt(0)
	v_mfma_f32_16x16x32_bf16 v[80:83], v[124:127], v[132:135], v[80:83]
	v_mul_f32_e64 v100, v100, v222
	v_mul_f32_e64 v101, v101, v223
	s_barrier
	v_pk_mul_f32 v[2:3], v[100:101], v[2:3]
	v_mfma_f32_16x16x32_bf16 v[78:81], v[140:143], v[136:139], v[80:83]
	ds_read_b128 v[4:7], v62 offset:33792
	ds_read_b128 v[22:25], v64 offset:33792
	ds_read_b128 v[26:29], v37
	ds_read_b128 v[38:41], v37 offset:64
	v_rcp_iflag_f32_e32 v82, v34
	v_rcp_iflag_f32_e32 v83, v35
	v_mfma_f32_16x16x32_bf16 v[78:81], v[148:151], v[156:159], v[78:81]
	v_mul_f32_e64 v82, v82, v218
	v_mul_f32_e64 v83, v83, v219
	v_pk_mul_f32 v[0:1], v[82:83], v[0:1]
	ds_read_b128 v[82:85], v63 offset:33792
	ds_read_b128 v[62:65], v65 offset:33792
	ds_read_b128 v[86:89], v66 offset:33792
	ds_read_b128 v[90:93], v68 offset:33792
	v_mfma_f32_16x16x32_bf16 v[0:3], v[104:107], v[108:111], v[0:3]
	v_mfma_f32_16x16x32_bf16 v[0:3], v[120:123], v[112:115], v[0:3]
	v_mfma_f32_16x16x32_bf16 v[0:3], v[128:131], v[132:135], v[0:3]
	v_mfma_f32_16x16x32_bf16 v[0:3], v[144:147], v[136:139], v[0:3]
	ds_read_b128 v[94:97], v37 offset:128
	ds_read_b128 v[98:101], v37 offset:192
	ds_read_b128 v[102:105], v67 offset:33792
	ds_read_b128 v[66:69], v69 offset:33792
	ds_read_b128 v[106:109], v70 offset:33792
	ds_read_b128 v[110:113], v71 offset:33792
	ds_read_b128 v[114:117], v37 offset:256
	ds_read_b128 v[118:121], v37 offset:320
	ds_read_b128 v[122:125], v72 offset:33792
	ds_read_b128 v[70:73], v73 offset:33792
	ds_read_b128 v[126:129], v74 offset:33792
	ds_read_b128 v[130:133], v75 offset:33792
	ds_read_b128 v[134:137], v37 offset:384
	ds_read_b128 v[138:141], v37 offset:448
	ds_read_b128 v[142:145], v76 offset:33792
	ds_read_b128 v[74:77], v77 offset:33792
	v_mfma_f32_16x16x32_bf16 v[0:3], v[152:155], v[156:159], v[0:3]
	v_mfma_f32_16x16x32_bf16 v[78:81], v[164:167], v[160:163], v[78:81]
	v_mfma_f32_16x16x32_bf16 v[0:3], v[168:171], v[160:163], v[0:3]
	v_mfma_f32_16x16x32_bf16 v[78:81], v[172:175], v[180:183], v[78:81]
	v_mfma_f32_16x16x32_bf16 v[0:3], v[176:179], v[180:183], v[0:3]
	v_mfma_f32_16x16x32_bf16 v[78:81], v[188:191], v[184:187], v[78:81]
	v_mfma_f32_16x16x32_bf16 v[0:3], v[192:195], v[184:187], v[0:3]
	v_cvt_f32_ubyte1_e32 v147, v32
	v_cvt_f32_ubyte0_e32 v146, v32
	v_cvt_f32_ubyte3_e32 v151, v32
	v_cvt_f32_ubyte2_e32 v150, v32
	v_rcp_iflag_f32_e32 v148, v146
	v_rcp_iflag_f32_e32 v149, v147
	v_rcp_iflag_f32_e32 v152, v150
	v_rcp_iflag_f32_e32 v153, v151
	s_mov_b32 s18, 0x3b800000
	v_pk_mul_f32 v[34:35], v[148:149], v[34:35]
	s_lshl_b32 s92, s12, 1
	v_pk_mul_f32 v[148:149], v[152:153], v[198:199]
	v_pk_mul_f32 v[0:1], v[34:35], v[0:1]
	v_pk_mul_f32 v[2:3], v[148:149], v[2:3]
	v_cvt_f32_ubyte1_e32 v35, v21
	v_cvt_f32_ubyte0_e32 v34, v21
	s_waitcnt lgkmcnt(14)
	v_mfma_f32_16x16x32_bf16 v[0:3], v[22:25], v[26:29], v[0:3]
	v_rcp_iflag_f32_e32 v22, v34
	v_rcp_iflag_f32_e32 v23, v35
	v_lshlrev_b32_e32 v32, 1, v14
	v_mfma_f32_16x16x32_bf16 v[0:3], v[62:65], v[38:41], v[0:3]
	v_cvt_f32_ubyte3_e32 v63, v21
	v_cvt_f32_ubyte2_e32 v62, v21
	v_rcp_iflag_f32_e32 v24, v62
	v_rcp_iflag_f32_e32 v25, v63
	v_pk_mul_f32 v[22:23], v[22:23], v[30:31]
	v_mfma_f32_16x16x32_bf16 v[0:3], v[90:93], v[94:97], v[0:3]
	v_mul_f32_e64 v22, v22, v78
	v_mul_f32_e64 v23, v23, v79
	v_pk_mul_f32 v[24:25], v[24:25], v[196:197]
	v_ashrrev_i32_e32 v21, 31, v20
	v_pk_mul_f32 v[24:25], v[24:25], v[80:81]
	s_waitcnt lgkmcnt(12)
	v_mfma_f32_16x16x32_bf16 v[0:3], v[66:69], v[98:101], v[0:3]
	v_mfma_f32_16x16x32_bf16 v[4:7], v[4:7], v[26:29], v[22:25]
	v_mul_f32_e64 v26, v62, s18
	v_mul_f32_e64 v27, v63, s18
	v_mfma_f32_16x16x32_bf16 v[4:7], v[82:85], v[38:41], v[4:7]
	v_mul_f32_e64 v24, v150, s18
	v_mul_f32_e64 v25, v151, s18
	v_pk_mul_f32 v[22:23], v[146:147], s[18:19] op_sel_hi:[1,0]
	s_waitcnt lgkmcnt(9)
	v_mfma_f32_16x16x32_bf16 v[0:3], v[110:113], v[114:117], v[0:3]
	v_mfma_f32_16x16x32_bf16 v[4:7], v[86:89], v[94:97], v[4:7]
	s_waitcnt lgkmcnt(6)
	v_mfma_f32_16x16x32_bf16 v[0:3], v[70:73], v[118:121], v[0:3]
	v_mfma_f32_16x16x32_bf16 v[4:7], v[102:105], v[98:101], v[4:7]
	s_waitcnt lgkmcnt(3)
	v_mfma_f32_16x16x32_bf16 v[0:3], v[130:133], v[134:137], v[0:3]
	v_mfma_f32_16x16x32_bf16 v[4:7], v[106:109], v[114:117], v[4:7]
	s_waitcnt lgkmcnt(0)
	v_mfma_f32_16x16x32_bf16 v[0:3], v[74:77], v[138:141], v[0:3]
	v_mfma_f32_16x16x32_bf16 v[4:7], v[122:125], v[118:121], v[4:7]
	s_nop 6
	v_mul_f32_e64 v24, v24, v2
	v_mul_f32_e64 v25, v25, v3
	v_mfma_f32_16x16x32_bf16 v[2:5], v[126:129], v[134:137], v[4:7]
	s_nop 2
	v_mul_f32_e64 v6, v22, v0
	v_mul_f32_e64 v7, v23, v1
	v_mfma_f32_16x16x32_bf16 v[0:3], v[142:145], v[138:141], v[2:5]
	v_mul_f32_e64 v22, v34, s18
	v_mul_f32_e64 v23, v35, s18
	s_nop 0
	v_lshlrev_b64 v[4:5], 11, v[20:21]
	v_lshl_add_u64 v[4:5], s[16:17], 0, v[4:5]
	v_lshl_add_u64 v[4:5], v[4:5], 0, s[92:93]
	s_nop 1
	v_pk_mul_f32 v[2:3], v[26:27], v[2:3]
	v_pk_mul_f32 v[0:1], v[22:23], v[0:1]
	v_lshl_add_u64 v[4:5], s[10:11], 1, v[4:5]
	v_lshl_add_u64 v[4:5], v[4:5], 0, v[32:33]
	v_cvt_pk_bf16_f32 v0, v0, v1
	v_cvt_pk_bf16_f32 v1, v2, v3
	global_store_dwordx2 v[4:5], v[0:1], off sc1
	v_cvt_pk_bf16_f32 v0, v6, v7
	v_cvt_pk_bf16_f32 v1, v24, v25
	global_store_dwordx2 v[4:5], v[0:1], off offset:32 sc1
	s_waitcnt vmcnt(0)
	s_barrier
	s_and_saveexec_b64 s[12:13], s[8:9]
	s_cbranch_execz .LBB0_1473
	s_mov_b64 s[18:19], exec
	v_mbcnt_lo_u32_b32 v0, s18, 0
	v_mbcnt_hi_u32_b32 v0, s19, v0
	v_cmp_eq_u32_e32 vcc, 0, v0
	s_and_b64 s[30:31], exec, vcc
	s_mov_b64 exec, s[30:31]
	s_cbranch_execz .LBB0_1473
	s_and_b32 s30, s29, -16
	s_add_i32 s30, s30, s22
	s_ashr_i32 s31, s30, 31
	s_lshl_b64 s[30:31], s[30:31], 2
	s_add_u32 s30, s20, s30
	s_addc_u32 s31, s21, s31
	s_bcnt1_i32_b64 s18, s[18:19]
	v_mov_b32_e32 v0, s18
	global_atomic_add v33, v0, s[30:31]
	s_branch .LBB0_1473

.LBB0_1813:
	s_or_b64 exec, exec, s[40:41]
	s_lshl_b32 s40, s55, 2
	s_and_b32 s41, s40, 0xffffffc0
	s_addk_i32 s41, 0x4000
	v_add_u32_e32 v0, s41, v29
	s_lshl_b32 s42, s55, 6
	v_ashrrev_i32_e32 v1, 31, v0
	s_and_b32 s40, s42, 0x3c0
	v_lshlrev_b64 v[0:1], 11, v[0:1]
	v_lshl_add_u64 v[12:13], v[8:9], 0, v[0:1]
	v_add_u32_e32 v0, s40, v29
	v_ashrrev_i32_e32 v1, 31, v0
	s_mov_b32 s43, 0x8000
	v_lshlrev_b64 v[0:1], 11, v[0:1]
	v_add_co_u32_e32 v16, vcc, s43, v12
	v_lshl_add_u64 v[14:15], v[10:11], 0, v[0:1]
	s_nop 0
	v_addc_co_u32_e32 v17, vcc, 0, v13, vcc
	v_add_co_u32_e32 v18, vcc, s43, v14
	s_mov_b32 s43, 0x18000
	s_nop 0
	v_addc_co_u32_e32 v19, vcc, 0, v15, vcc
	v_add_co_u32_e32 v20, vcc, s82, v12
	s_nop 1
	v_addc_co_u32_e32 v21, vcc, 0, v13, vcc
	v_add_co_u32_e32 v22, vcc, s82, v14
	s_barrier
	s_nop 0
	v_addc_co_u32_e32 v23, vcc, 0, v15, vcc
	v_add_co_u32_e32 v24, vcc, s43, v12
	s_nop 1
	v_addc_co_u32_e32 v25, vcc, 0, v13, vcc
	v_add_co_u32_e32 v26, vcc, s43, v14
	global_load_dwordx4 v[0:3], v[12:13], off
	global_load_dwordx4 v[4:7], v[14:15], off
	global_load_dwordx4 v[56:59], v[16:17], off
	global_load_dwordx4 v[60:63], v[18:19], off
	global_load_dwordx4 v[64:67], v[20:21], off
	global_load_dwordx4 v[68:71], v[22:23], off
	v_addc_co_u32_e32 v27, vcc, 0, v15, vcc
	global_load_dwordx4 v[72:75], v[24:25], off
	global_load_dwordx4 v[76:79], v[26:27], off
	v_add_u32_e32 v55, 0, v31
	s_barrier
	v_add_u32_e32 v185, 0, v35
	v_add_u32_e32 v187, 0, v39
	v_add_u32_e32 v189, 0, v41
	v_add_u32_e32 v191, 0, v43
	v_add_u32_e32 v193, 0, v45
	v_add_u32_e32 v195, 0, v47
	v_add_u32_e32 v197, 0, v49
	v_add_u32_e32 v184, 0, v34
	v_add_u32_e32 v186, 0, v38
	v_add_u32_e32 v188, 0, v40
	v_add_u32_e32 v190, 0, v42
	v_add_u32_e32 v192, 0, v44
	v_add_u32_e32 v194, 0, v46
	v_add_u32_e32 v196, 0, v48
	v_add_u32_e32 v198, 0, v50
	v_add_u32_e32 v199, 0, v51
	v_add_u32_e32 v201, 0, v52
	s_waitcnt vmcnt(7)
	ds_write_b128 v55, v[0:3]
	s_waitcnt vmcnt(6)
	ds_write_b128 v55, v[4:7] offset:33792
	s_waitcnt vmcnt(5)
	ds_write_b128 v55, v[56:59] offset:8448
	s_waitcnt vmcnt(4)
	ds_write_b128 v55, v[60:63] offset:42240
	s_waitcnt vmcnt(3)
	ds_write_b128 v55, v[64:67] offset:16896
	s_waitcnt vmcnt(2)
	ds_write_b128 v55, v[68:71] offset:50688
	s_waitcnt vmcnt(1)
	ds_write_b128 v55, v[72:75] offset:25344
	s_waitcnt vmcnt(0)
	ds_write_b128 v55, v[76:79] offset:59136
	global_load_dwordx4 v[56:59], v[26:27], off offset:512
	global_load_dwordx4 v[60:63], v[24:25], off offset:512
	global_load_dwordx4 v[64:67], v[22:23], off offset:512
	global_load_dwordx4 v[68:71], v[20:21], off offset:512
	global_load_dwordx4 v[72:75], v[18:19], off offset:512
	global_load_dwordx4 v[76:79], v[16:17], off offset:512
	global_load_dwordx4 v[80:83], v[14:15], off offset:512
	global_load_dwordx4 v[84:87], v[12:13], off offset:512
	s_waitcnt lgkmcnt(0)
	s_barrier
	ds_read_b128 v[0:3], v185 offset:33792
	ds_read_b128 v[4:7], v186 offset:33792
	ds_read_b128 v[88:91], v184
	ds_read_b128 v[92:95], v184 offset:64
	ds_read_b128 v[96:99], v187 offset:33792
	ds_read_b128 v[100:103], v188 offset:33792
	ds_read_b128 v[104:107], v189 offset:33792
	ds_read_b128 v[108:111], v190 offset:33792
	ds_read_b128 v[112:115], v184 offset:128
	ds_read_b128 v[116:119], v184 offset:192
	ds_read_b128 v[120:123], v191 offset:33792
	ds_read_b128 v[124:127], v192 offset:33792
	ds_read_b128 v[128:131], v193 offset:33792
	ds_read_b128 v[132:135], v194 offset:33792
	ds_read_b128 v[136:139], v184 offset:256
	ds_read_b128 v[140:143], v184 offset:320
	ds_read_b128 v[144:147], v195 offset:33792
	ds_read_b128 v[148:151], v196 offset:33792
	ds_read_b128 v[152:155], v197 offset:33792
	ds_read_b128 v[156:159], v198 offset:33792
	ds_read_b128 v[160:163], v184 offset:384
	ds_read_b128 v[164:167], v184 offset:448
	ds_read_b128 v[168:171], v199 offset:33792
	ds_read_b128 v[172:175], v201 offset:33792
	v_add_u32_e32 v202, s59, v31
	v_add_u32_e32 v203, s58, v31
	s_waitcnt vmcnt(0)
	ds_write_b128 v202, v[84:87]
	ds_write_b128 v203, v[80:83]
	ds_write_b128 v202, v[76:79] offset:8448
	ds_write_b128 v203, v[72:75] offset:8448
	ds_write_b128 v202, v[68:71] offset:16896
	ds_write_b128 v203, v[64:67] offset:16896
	ds_write_b128 v202, v[60:63] offset:25344
	ds_write_b128 v203, v[56:59] offset:25344
	global_load_dwordx4 v[56:59], v[26:27], off offset:1024
	global_load_dwordx4 v[60:63], v[24:25], off offset:1024
	global_load_dwordx4 v[64:67], v[22:23], off offset:1024
	global_load_dwordx4 v[68:71], v[20:21], off offset:1024
	global_load_dwordx4 v[72:75], v[18:19], off offset:1024
	global_load_dwordx4 v[76:79], v[16:17], off offset:1024
	global_load_dwordx4 v[80:83], v[14:15], off offset:1024
	global_load_dwordx4 v[84:87], v[12:13], off offset:1024
	s_waitcnt lgkmcnt(0)
	s_barrier
	v_mfma_f32_16x16x32_bf16 v[0:3], v[0:3], v[88:91], 0
	v_add_u32_e32 v204, s59, v34
	v_add_u32_e32 v205, s58, v35
	v_add_u32_e32 v206, s58, v38
	v_mfma_f32_16x16x32_bf16 v[4:7], v[4:7], v[88:91], 0
	v_add_u32_e32 v207, s58, v39
	v_add_u32_e32 v208, s58, v40
	v_add_u32_e32 v209, s58, v41
	v_mfma_f32_16x16x32_bf16 v[0:3], v[96:99], v[92:95], v[0:3]
	v_add_u32_e32 v210, s58, v42
	v_add_u32_e32 v211, s58, v43
	v_add_u32_e32 v212, s58, v44
	v_mfma_f32_16x16x32_bf16 v[4:7], v[100:103], v[92:95], v[4:7]
	v_add_u32_e32 v213, s58, v45
	v_add_u32_e32 v214, s58, v46
	v_add_u32_e32 v215, s58, v47
	v_mfma_f32_16x16x32_bf16 v[0:3], v[104:107], v[112:115], v[0:3]
	v_add_u32_e32 v218, s58, v48
	v_add_u32_e32 v219, s58, v49
	v_add_u32_e32 v220, s58, v50
	v_mfma_f32_16x16x32_bf16 v[4:7], v[108:111], v[112:115], v[4:7]
	ds_read_b128 v[88:91], v204
	ds_read_b128 v[92:95], v205
	ds_read_b128 v[96:99], v206
	ds_read_b128 v[100:103], v204 offset:64
	v_mfma_f32_16x16x32_bf16 v[0:3], v[120:123], v[116:119], v[0:3]
	ds_read_b128 v[104:107], v207
	ds_read_b128 v[108:111], v208
	ds_read_b128 v[112:115], v204 offset:128
	v_add_u32_e32 v221, s58, v51
	v_mfma_f32_16x16x32_bf16 v[4:7], v[124:127], v[116:119], v[4:7]
	ds_read_b128 v[116:119], v209
	ds_read_b128 v[120:123], v210
	ds_read_b128 v[124:127], v204 offset:192
	v_add_u32_e32 v222, s58, v52
	v_mfma_f32_16x16x32_bf16 v[0:3], v[128:131], v[136:139], v[0:3]
	ds_read_b128 v[128:131], v211
	v_mfma_f32_16x16x32_bf16 v[4:7], v[132:135], v[136:139], v[4:7]
	ds_read_b128 v[132:135], v212
	ds_read_b128 v[136:139], v204 offset:256
	v_mfma_f32_16x16x32_bf16 v[0:3], v[144:147], v[140:143], v[0:3]
	v_mfma_f32_16x16x32_bf16 v[4:7], v[148:151], v[140:143], v[4:7]
	ds_read_b128 v[140:143], v213
	ds_read_b128 v[144:147], v214
	ds_read_b128 v[148:151], v204 offset:320
	v_mfma_f32_16x16x32_bf16 v[0:3], v[152:155], v[160:163], v[0:3]
	ds_read_b128 v[152:155], v215
	v_mfma_f32_16x16x32_bf16 v[4:7], v[156:159], v[160:163], v[4:7]
	ds_read_b128 v[156:159], v218
	ds_read_b128 v[160:163], v204 offset:384
	v_mfma_f32_16x16x32_bf16 v[0:3], v[168:171], v[164:167], v[0:3]
	v_mfma_f32_16x16x32_bf16 v[4:7], v[172:175], v[164:167], v[4:7]
	ds_read_b128 v[164:167], v219
	ds_read_b128 v[168:171], v220
	ds_read_b128 v[172:175], v204 offset:448
	ds_read_b128 v[176:179], v221
	ds_read_b128 v[180:183], v222
	s_waitcnt vmcnt(0)
	ds_write_b128 v55, v[84:87]
	ds_write_b128 v55, v[80:83] offset:33792
	ds_write_b128 v55, v[76:79] offset:8448
	ds_write_b128 v55, v[72:75] offset:42240
	ds_write_b128 v55, v[68:71] offset:16896
	ds_write_b128 v55, v[64:67] offset:50688
	ds_write_b128 v55, v[60:63] offset:25344
	ds_write_b128 v55, v[56:59] offset:59136
	global_load_dwordx4 v[56:59], v[26:27], off offset:1536
	s_nop 0
	global_load_dwordx4 v[24:27], v[24:25], off offset:1536
	s_nop 0
	global_load_dwordx4 v[60:63], v[22:23], off offset:1536
	s_nop 0
	global_load_dwordx4 v[20:23], v[20:21], off offset:1536
	s_nop 0
	global_load_dwordx4 v[64:67], v[18:19], off offset:1536
	s_nop 0
	global_load_dwordx4 v[16:19], v[16:17], off offset:1536
	s_nop 0
	global_load_dwordx4 v[68:71], v[14:15], off offset:1536
	s_nop 0
	global_load_dwordx4 v[12:15], v[12:13], off offset:1536
	s_waitcnt lgkmcnt(0)
	s_barrier
	v_mfma_f32_16x16x32_bf16 v[0:3], v[92:95], v[88:91], v[0:3]
	ds_read_b128 v[72:75], v185 offset:33792
	ds_read_b128 v[76:79], v186 offset:33792
	ds_read_b128 v[80:83], v184
	ds_read_b128 v[84:87], v184 offset:64
	v_mfma_f32_16x16x32_bf16 v[4:7], v[96:99], v[88:91], v[4:7]
	v_mfma_f32_16x16x32_bf16 v[0:3], v[104:107], v[100:103], v[0:3]
	v_mfma_f32_16x16x32_bf16 v[4:7], v[108:111], v[100:103], v[4:7]
	ds_read_b128 v[88:91], v187 offset:33792
	ds_read_b128 v[92:95], v188 offset:33792
	ds_read_b128 v[96:99], v189 offset:33792
	ds_read_b128 v[100:103], v190 offset:33792
	v_mfma_f32_16x16x32_bf16 v[0:3], v[116:119], v[112:115], v[0:3]
	v_mfma_f32_16x16x32_bf16 v[4:7], v[120:123], v[112:115], v[4:7]
	ds_read_b128 v[104:107], v184 offset:128
	ds_read_b128 v[108:111], v184 offset:192
	ds_read_b128 v[112:115], v191 offset:33792
	ds_read_b128 v[116:119], v192 offset:33792
	v_mfma_f32_16x16x32_bf16 v[0:3], v[128:131], v[124:127], v[0:3]
	v_mfma_f32_16x16x32_bf16 v[4:7], v[132:135], v[124:127], v[4:7]
	ds_read_b128 v[120:123], v193 offset:33792
	ds_read_b128 v[124:127], v194 offset:33792
	ds_read_b128 v[128:131], v184 offset:256
	ds_read_b128 v[132:135], v184 offset:320
	v_mfma_f32_16x16x32_bf16 v[0:3], v[140:143], v[136:139], v[0:3]
	v_mfma_f32_16x16x32_bf16 v[4:7], v[144:147], v[136:139], v[4:7]
	v_mfma_f32_16x16x32_bf16 v[0:3], v[152:155], v[148:151], v[0:3]
	v_mfma_f32_16x16x32_bf16 v[4:7], v[156:159], v[148:151], v[4:7]
	ds_read_b128 v[136:139], v195 offset:33792
	ds_read_b128 v[140:143], v196 offset:33792
	ds_read_b128 v[144:147], v197 offset:33792
	ds_read_b128 v[148:151], v198 offset:33792
	v_mfma_f32_16x16x32_bf16 v[0:3], v[164:167], v[160:163], v[0:3]
	v_mfma_f32_16x16x32_bf16 v[4:7], v[168:171], v[160:163], v[4:7]
	ds_read_b128 v[152:155], v184 offset:384
	ds_read_b128 v[156:159], v184 offset:448
	ds_read_b128 v[160:163], v199 offset:33792
	ds_read_b128 v[164:167], v201 offset:33792
	v_mfma_f32_16x16x32_bf16 v[0:3], v[176:179], v[172:175], v[0:3]
	v_mfma_f32_16x16x32_bf16 v[4:7], v[180:183], v[172:175], v[4:7]
	s_waitcnt lgkmcnt(14)
	v_mfma_f32_16x16x32_bf16 v[0:3], v[72:75], v[80:83], v[0:3]
	s_waitcnt vmcnt(0)
	ds_write_b128 v202, v[12:15]
	ds_write_b128 v203, v[68:71]
	ds_write_b128 v202, v[16:19] offset:8448
	ds_write_b128 v203, v[64:67] offset:8448
	ds_write_b128 v202, v[20:23] offset:16896
	ds_write_b128 v203, v[60:63] offset:16896
	ds_write_b128 v202, v[24:27] offset:25344
	ds_write_b128 v203, v[56:59] offset:25344
	v_mfma_f32_16x16x32_bf16 v[4:7], v[76:79], v[80:83], v[4:7]
	s_waitcnt lgkmcnt(0)
	s_barrier
	v_mfma_f32_16x16x32_bf16 v[0:3], v[88:91], v[84:87], v[0:3]
	ds_read_b128 v[12:15], v205
	ds_read_b128 v[16:19], v206
	ds_read_b128 v[20:23], v204
	ds_read_b128 v[24:27], v204 offset:64
	ds_read_b128 v[56:59], v207
	ds_read_b128 v[60:63], v208
	ds_read_b128 v[64:67], v209
	ds_read_b128 v[68:71], v210
	v_mfma_f32_16x16x32_bf16 v[4:7], v[92:95], v[84:87], v[4:7]
	ds_read_b128 v[72:75], v204 offset:128
	ds_read_b128 v[76:79], v204 offset:192
	ds_read_b128 v[80:83], v211
	ds_read_b128 v[84:87], v212
	v_mfma_f32_16x16x32_bf16 v[0:3], v[96:99], v[104:107], v[0:3]
	v_mfma_f32_16x16x32_bf16 v[4:7], v[100:103], v[104:107], v[4:7]
	ds_read_b128 v[88:91], v213
	ds_read_b128 v[92:95], v214
	ds_read_b128 v[96:99], v204 offset:256
	ds_read_b128 v[100:103], v204 offset:320
	v_mfma_f32_16x16x32_bf16 v[0:3], v[112:115], v[108:111], v[0:3]
	v_mfma_f32_16x16x32_bf16 v[4:7], v[116:119], v[108:111], v[4:7]
	ds_read_b128 v[104:107], v215
	ds_read_b128 v[108:111], v218
	ds_read_b128 v[112:115], v219
	ds_read_b128 v[116:119], v220
	v_mfma_f32_16x16x32_bf16 v[0:3], v[120:123], v[128:131], v[0:3]
	v_mfma_f32_16x16x32_bf16 v[4:7], v[124:127], v[128:131], v[4:7]
	v_mfma_f32_16x16x32_bf16 v[0:3], v[136:139], v[132:135], v[0:3]
	v_mfma_f32_16x16x32_bf16 v[4:7], v[140:143], v[132:135], v[4:7]
	ds_read_b128 v[120:123], v204 offset:384
	ds_read_b128 v[124:127], v204 offset:448
	ds_read_b128 v[128:131], v221
	ds_read_b128 v[132:135], v222
	v_mfma_f32_16x16x32_bf16 v[0:3], v[144:147], v[152:155], v[0:3]
	v_mfma_f32_16x16x32_bf16 v[4:7], v[148:151], v[152:155], v[4:7]
	v_mfma_f32_16x16x32_bf16 v[0:3], v[160:163], v[156:159], v[0:3]
	v_mfma_f32_16x16x32_bf16 v[4:7], v[164:167], v[156:159], v[4:7]
	s_waitcnt lgkmcnt(14)
	v_mfma_f32_16x16x32_bf16 v[0:3], v[12:15], v[20:23], v[0:3]
	s_lshl_b32 s92, s40, 1
	v_mfma_f32_16x16x32_bf16 v[0:3], v[56:59], v[24:27], v[0:3]
	v_mfma_f32_16x16x32_bf16 v[4:7], v[16:19], v[20:23], v[4:7]
	v_mfma_f32_16x16x32_bf16 v[0:3], v[64:67], v[72:75], v[0:3]
	v_mfma_f32_16x16x32_bf16 v[4:7], v[60:63], v[24:27], v[4:7]
	s_waitcnt lgkmcnt(13)
	v_mfma_f32_16x16x32_bf16 v[0:3], v[80:83], v[76:79], v[0:3]
	v_mfma_f32_16x16x32_bf16 v[4:7], v[68:71], v[72:75], v[4:7]
	s_waitcnt lgkmcnt(9)
	v_mfma_f32_16x16x32_bf16 v[0:3], v[88:91], v[96:99], v[0:3]
	v_mfma_f32_16x16x32_bf16 v[4:7], v[84:87], v[76:79], v[4:7]
	s_waitcnt lgkmcnt(7)
	v_mfma_f32_16x16x32_bf16 v[12:15], v[104:107], v[100:103], v[0:3]
	v_mfma_f32_16x16x32_bf16 v[4:7], v[92:95], v[96:99], v[4:7]
	s_nop 3
	v_or_b32_e32 v0, s41, v30
	v_ashrrev_i32_e32 v1, 31, v0
	s_waitcnt lgkmcnt(3)
	v_mfma_f32_16x16x32_bf16 v[12:15], v[112:115], v[120:123], v[12:15]
	v_mfma_f32_16x16x32_bf16 v[2:5], v[108:111], v[100:103], v[4:7]
	s_waitcnt lgkmcnt(1)
	v_mfma_f32_16x16x32_bf16 v[12:15], v[128:131], v[124:127], v[12:15]
	s_nop 0
	v_lshlrev_b64 v[6:7], 11, v[0:1]
	v_lshl_add_u64 v[6:7], s[10:11], 0, v[6:7]
	v_lshl_add_u64 v[16:17], v[6:7], 0, s[92:93]
	v_mfma_f32_16x16x32_bf16 v[2:5], v[116:119], v[120:123], v[2:5]
	s_nop 2
	v_mul_f32_e32 v6, v13, v13
	v_mul_f32_e32 v7, v15, v15
	v_fmac_f32_e32 v6, v12, v12
	v_fmac_f32_e32 v7, v14, v14
	v_add_f32_e32 v18, v6, v7
	s_waitcnt lgkmcnt(0)
	v_mfma_f32_16x16x32_bf16 v[4:7], v[132:135], v[124:127], v[2:5]
	v_cvt_pk_bf16_f32 v12, v12, v13
	v_cvt_pk_bf16_f32 v13, v14, v15
	s_nop 5
	v_mul_f32_e32 v2, v5, v5
	v_mul_f32_e32 v3, v7, v7
	v_fmac_f32_e32 v2, v4, v4
	v_fmac_f32_e32 v3, v6, v6
	v_add_f32_e32 v2, v2, v3
	v_add_f32_e32 v18, v18, v2
	ds_bpermute_b32 v19, v53, v18
	v_lshl_add_u64 v[2:3], s[12:13], 1, v[16:17]
	v_lshl_add_u64 v[16:17], v[2:3], 0, v[32:33]
	v_cvt_pk_bf16_f32 v4, v4, v5
	v_cvt_pk_bf16_f32 v5, v6, v7
	s_waitcnt lgkmcnt(0)
	v_add_f32_e32 v2, v18, v19
	ds_bpermute_b32 v3, v54, v2
	global_store_dwordx2 v[16:17], v[12:13], off sc1
	global_store_dwordx2 v[16:17], v[4:5], off offset:32 sc1
	s_and_saveexec_b64 s[40:41], s[8:9]
	s_cbranch_execz .LBB0_1815
	v_lshlrev_b64 v[0:1], 7, v[0:1]
	s_lshr_b32 s42, s42, 3
	v_lshl_add_u64 v[0:1], s[16:17], 0, v[0:1]
	s_and_b32 s92, s42, 0x78
	v_lshl_add_u64 v[0:1], v[0:1], 0, s[92:93]
	s_waitcnt lgkmcnt(0)
	v_add_f32_e32 v2, v2, v3
	v_lshl_add_u64 v[0:1], s[34:35], 2, v[0:1]
	global_store_dword v[0:1], v2, off sc1
